# fused residual+rmsnorm epilogue: redundant agent-scope acquire after the partial-sum exchange removed (partials are sc1-stored and sc1-loaded)
# speedup vs baseline: 1.0073x; 1.0009x over previous
.LBB0_446:
.LBB0_447:
	s_or_b64 exec, exec, s[0:1]
	s_barrier
	s_and_saveexec_b64 s[0:1], s[8:9]
	s_cbranch_execz .LBB0_449
	s_lshl_b32 s4, s6, 2
	s_ashr_i32 s5, s4, 31
	s_lshl_b64 s[4:5], s[4:5], 10
	s_add_u32 s4, s21, s4
	s_addc_u32 s5, s38, s5
	v_lshl_add_u64 v[146:147], v[212:213], 2, s[4:5]
	global_load_dword v148, v[146:147], off sc1
	global_load_dword v150, v[146:147], off offset:1024 sc1
	global_load_dword v149, v[146:147], off offset:2048 sc1
	global_load_dword v151, v[146:147], off offset:3072 sc1
	s_waitcnt vmcnt(0)
	v_pk_add_f32 v[146:147], v[148:149], v[150:151]
	s_nop 0
	v_add_f32_e32 v146, v146, v147
	v_mov_b32_e32 v147, 0x358637bd
	v_fmamk_f32 v146, v146, 0x3a800000, v147
	v_mul_f32_e32 v147, 0x4b800000, v146
	v_cmp_gt_f32_e32 vcc, s69, v146
	s_nop 1
	v_cndmask_b32_e32 v146, v146, v147, vcc
	v_rsq_f32_e32 v146, v146
	s_nop 0
	v_mul_f32_e32 v147, 0x45800000, v146
	v_cndmask_b32_e32 v146, v146, v147, vcc
	v_mov_b32_e32 v147, 0x21000
	v_lshl_add_u32 v147, v212, 2, v147
	ds_write_b32 v147, v146

.LBB0_1423:
.LBB0_1424:
	s_or_b64 exec, exec, s[0:1]
	s_barrier
	s_and_saveexec_b64 s[0:1], s[8:9]
	s_cbranch_execz .LBB0_1426
	s_lshl_b32 s4, s6, 2
	s_ashr_i32 s5, s4, 31
	s_lshl_b64 s[4:5], s[4:5], 10
	s_add_u32 s4, s17, s4
	s_addc_u32 s5, s20, s5
	v_lshl_add_u64 v[146:147], v[212:213], 2, s[4:5]
	global_load_dword v148, v[146:147], off sc1
	global_load_dword v150, v[146:147], off offset:1024 sc1
	global_load_dword v149, v[146:147], off offset:2048 sc1
	global_load_dword v151, v[146:147], off offset:3072 sc1
	s_waitcnt vmcnt(0)
	v_pk_add_f32 v[146:147], v[148:149], v[150:151]
	s_nop 0
	v_add_f32_e32 v146, v146, v147
	v_mov_b32_e32 v147, 0x358637bd
	v_fmamk_f32 v146, v146, 0x3a800000, v147
	v_mul_f32_e32 v147, 0x4b800000, v146
	v_cmp_gt_f32_e32 vcc, s69, v146
	s_nop 1
	v_cndmask_b32_e32 v146, v146, v147, vcc
	v_rsq_f32_e32 v146, v146
	s_nop 0
	v_mul_f32_e32 v147, 0x45800000, v146
	v_cndmask_b32_e32 v146, v146, v147, vcc
	v_mov_b32_e32 v147, 0x21000
	v_lshl_add_u32 v147, v212, 2, v147
	ds_write_b32 v147, v146

.LBB0_1691:
.LBB0_1692:
	s_or_b64 exec, exec, s[0:1]
	s_barrier
	s_and_saveexec_b64 s[0:1], s[6:7]
	s_cbranch_execz .LBB0_1694
	s_lshl_b32 s4, s14, 2
	s_ashr_i32 s5, s4, 31
	s_lshl_b64 s[4:5], s[4:5], 10
	v_readlane_b32 s2, v253, 13
	s_add_u32 s4, s2, s4
	v_readlane_b32 s2, v253, 14
	s_addc_u32 s5, s2, s5
	v_lshl_add_u64 v[78:79], v[214:215], 2, s[4:5]
	global_load_dword v80, v[78:79], off sc1
	global_load_dword v86, v[78:79], off offset:1024 sc1
	global_load_dword v81, v[78:79], off offset:2048 sc1
	global_load_dword v87, v[78:79], off offset:3072 sc1
	s_waitcnt vmcnt(0)
	v_pk_add_f32 v[78:79], v[80:81], v[86:87]
	s_nop 0
	v_add_f32_e32 v0, v78, v79
	v_mov_b32_e32 v78, 0x358637bd
	v_fmamk_f32 v0, v0, 0x3a800000, v78
	v_mul_f32_e32 v78, 0x4b800000, v0
	v_cmp_gt_f32_e32 vcc, s69, v0
	s_nop 1
	v_cndmask_b32_e32 v0, v0, v78, vcc
	v_rsq_f32_e32 v0, v0
	s_nop 0
	v_mul_f32_e32 v78, 0x45800000, v0
	v_cndmask_b32_e32 v0, v0, v78, vcc
	v_mov_b32_e32 v78, 0x21000
	v_lshl_add_u32 v78, v214, 2, v78
	ds_write_b32 v78, v0

.LBB0_1754:
.LBB0_1755:
	s_or_b64 exec, exec, s[0:1]
	s_barrier
	s_and_saveexec_b64 s[0:1], s[4:5]
	s_cbranch_execz .LBB0_1757
	s_lshl_b32 s4, s10, 2
	s_ashr_i32 s5, s4, 31
	s_lshl_b64 s[4:5], s[4:5], 10
	v_readlane_b32 s6, v253, 17
	s_add_u32 s4, s6, s4
	v_readlane_b32 s6, v253, 18
	s_addc_u32 s5, s6, s5
	v_lshl_add_u64 v[146:147], v[212:213], 2, s[4:5]
	global_load_dword v148, v[146:147], off sc1
	global_load_dword v150, v[146:147], off offset:1024 sc1
	global_load_dword v149, v[146:147], off offset:2048 sc1
	global_load_dword v151, v[146:147], off offset:3072 sc1
	s_waitcnt vmcnt(0)
	v_pk_add_f32 v[146:147], v[148:149], v[150:151]
	s_nop 0
	v_add_f32_e32 v146, v146, v147
	v_mov_b32_e32 v147, 0x358637bd
	v_fmamk_f32 v146, v146, 0x3a800000, v147
	v_mul_f32_e32 v147, 0x4b800000, v146
	v_cmp_gt_f32_e32 vcc, s69, v146
	s_nop 1
	v_cndmask_b32_e32 v146, v146, v147, vcc
	v_rsq_f32_e32 v146, v146
	s_nop 0
	v_mul_f32_e32 v147, 0x45800000, v146
	v_cndmask_b32_e32 v146, v146, v147, vcc
	v_mov_b32_e32 v147, 0x21000
	v_lshl_add_u32 v147, v212, 2, v147
	ds_write_b32 v147, v146
